# placement: FFN-F2 loop head at 44 mod 64 (odd dword phase)
# baseline (speedup 1.0000x reference)
.LBB0_1051:
	v_lshrrev_b32_e32 v15, 1, v14
	v_and_b32_e32 v15, 24, v15
	v_and_b32_e32 v221, 15, v14
	v_lshlrev_b32_e32 v16, 1, v15
	v_lshlrev_b32_e32 v14, 2, v14
	s_lshl_b32 s3, s3, 5
	s_lshl_b32 s60, s4, 6
	v_lshl_or_b32 v16, v221, 6, v16
	s_lshl_b32 s4, s4, 13
	v_and_b32_e32 v14, 32, v14
	s_and_b32 s3, s3, 0x60
	s_add_i32 m0, s42, 0x18000
	v_lshl_add_u64 v[6:7], v[6:7], 0, s[74:75]
	v_bitop3_b32 v17, v16, s4, v14 bitop3:0xde
	s_lshl_b32 s4, s3, 7
	s_waitcnt vmcnt(2)
	s_barrier
	global_load_lds_dwordx4 v[6:7], off
	v_lshl_add_u64 v[4:5], v[4:5], 0, s[74:75]
	s_add_i32 m0, s42, 0x1a000
	s_add_i32 s61, s42, 0x8000
	s_add_i32 s64, s42, 0xa000
	v_bitop3_b32 v222, v16, s4, v14 bitop3:0xde
	global_load_lds_dwordx4 v[4:5], off
	v_lshl_add_u64 v[0:1], v[0:1], 0, s[74:75]
	s_mov_b32 m0, s61
	s_add_u32 s4, s12, 0x80080
	global_load_lds_dwordx4 v[0:1], off
	v_lshl_add_u64 v[0:1], v[2:3], 0, s[74:75]
	s_mov_b32 m0, s64
	s_addc_u32 s5, s13, 0
	global_load_lds_dwordx4 v[0:1], off
	s_add_i32 m0, s42, 0x1c000
	v_lshl_add_u64 v[0:1], s[4:5], 0, v[176:177]
	global_load_lds_dwordx4 v[0:1], off
	v_lshl_add_u64 v[0:1], s[4:5], 0, v[178:179]
	s_add_i32 m0, s42, 0x1e000
	s_cmpk_lt_u32 s2, 0x100
	global_load_lds_dwordx4 v[0:1], off
	v_lshlrev_b32_e32 v0, 15, v12
	v_and_b32_e32 v0, 0xffff0000, v0
	v_lshl_add_u32 v0, v11, 12, v0
	v_and_b32_e32 v1, 1, v12
	v_lshl_or_b32 v0, v1, 6, v0
	v_lshl_add_u32 v184, v13, 1, v0
	v_lshlrev_b32_e32 v0, 15, v8
	s_cselect_b64 s[40:41], -1, 0
	s_add_u32 s46, s18, 0x5800
	v_and_b32_e32 v0, 0xffff0000, v0
	s_waitcnt vmcnt(6)
	s_addc_u32 s47, s19, 0
	v_lshl_add_u32 v0, v9, 12, v0
	v_and_b32_e32 v1, 1, v8
	s_add_u32 s48, s18, 0xb000
	v_lshl_or_b32 v0, v1, 6, v0
	v_readlane_b32 s14, v254, 39
	s_mov_b32 s65, 0
	v_cmp_eq_u32_e64 s[4:5], 0, v221
	v_cmp_eq_u32_e64 s[6:7], 15, v221
	s_addc_u32 s49, s19, 0
	v_or_b32_e32 v223, s3, v15
	v_mov_b32_e32 v185, v177
	v_lshl_add_u32 v186, v10, 1, v0
	v_mov_b32_e32 v187, v177
	v_add_u32_e32 v224, 0, v17
	v_readlane_b32 s2, v254, 38
	s_mov_b32 s3, s14
	s_barrier
	v_readlane_b32 s15, v254, 40
	s_branch .LBB0_1054
	s_nop 0

.LBB0_1154:
	s_lshl_b32 s6, s20, 1
	s_or_b32 s13, s6, 1
	s_mul_i32 s7, s13, 0x3000
	s_mul_hi_u32 s6, s13, 0x3000
	s_add_u32 s7, s18, s7
	s_addc_u32 s6, s19, s6
	s_add_u32 s42, s7, 0x20000
	s_addc_u32 s43, s6, 0
	s_lshl_b32 s72, s20, 11
	s_lshl_b64 s[6:7], s[72:73], 2
	s_waitcnt lgkmcnt(0)
	s_add_u32 s36, s4, s6
	s_addc_u32 s37, s5, s7
	s_add_u32 s14, s18, 0x40000
	s_mul_i32 s4, s20, 0xc000
	s_addc_u32 s15, s19, 0
	s_add_i32 s6, s4, 0xc000
	s_and_b64 s[4:5], exec, s[8:9]
	s_cselect_b32 s72, 0, s6
	s_lshl_b64 s[4:5], s[72:73], 2
	s_add_u32 s6, s14, s4
	s_addc_u32 s7, s15, s5
	s_mul_hi_u32 s4, s13, 0x18000
	s_mul_i32 s13, s13, 0x18000
	s_add_u32 s40, s14, s13
	s_addc_u32 s41, s15, s4
	s_add_u32 s46, s18, 0x100000
	s_addc_u32 s47, s19, 0
	s_add_u32 s48, s18, 0x10200
	s_addc_u32 s49, s19, 0
	s_and_b32 s8, s3, 3
	s_lshl_b32 s3, s12, 6
	s_lshl_b32 s9, s12, 13
	s_lshl_b32 s13, s8, 12
	s_add_u32 s18, s18, 0x8800000
	s_addc_u32 s19, s19, 0
	s_add_i32 m0, s28, 0x18000
	v_lshl_add_u64 v[6:7], v[6:7], 0, s[74:75]
	s_waitcnt vmcnt(2)
	s_barrier
	global_load_lds_dwordx4 v[6:7], off
	v_lshl_add_u64 v[4:5], v[4:5], 0, s[74:75]
	s_add_i32 m0, s28, 0x1a000
	s_add_i32 s44, s28, 0x8000
	s_add_i32 s45, s28, 0xa000
	global_load_lds_dwordx4 v[4:5], off
	v_lshl_add_u64 v[0:1], v[0:1], 0, s[74:75]
	s_mov_b32 m0, s44
	s_add_u32 s4, s30, 0x160080
	global_load_lds_dwordx4 v[0:1], off
	v_lshl_add_u64 v[0:1], v[2:3], 0, s[74:75]
	s_mov_b32 m0, s45
	s_addc_u32 s5, s31, 0
	global_load_lds_dwordx4 v[0:1], off
	s_add_i32 m0, s28, 0x1c000
	v_lshl_add_u64 v[0:1], s[4:5], 0, v[176:177]
	global_load_lds_dwordx4 v[0:1], off
	v_lshl_add_u64 v[0:1], s[4:5], 0, v[182:183]
	s_add_i32 m0, s28, 0x1e000
	v_lshlrev_b32_e32 v5, 2, v15
	global_load_lds_dwordx4 v[0:1], off
	v_and_b32_e32 v0, 15, v15
	v_bfe_u32 v1, v15, 4, 2
	v_or_b32_e32 v184, s3, v0
	v_lshlrev_b32_e32 v2, 4, v1
	v_lshlrev_b32_e32 v3, 2, v184
	s_cmpk_lt_u32 s2, 0x100
	v_lshl_or_b32 v2, v0, 6, v2
	v_and_b32_e32 v4, 32, v3
	v_and_b32_e32 v5, 32, v5
	s_cselect_b64 s[52:53], -1, 0
	s_add_i32 s2, s3, 0x80
	v_bitop3_b32 v4, v2, s9, v4 bitop3:0xde
	v_bitop3_b32 v204, v2, s13, v5 bitop3:0xde
	v_lshlrev_b32_e32 v2, 4, v0
	v_ashrrev_i32_e32 v185, 31, v184
	v_or_b32_e32 v0, s2, v0
	s_ashr_i32 s2, s3, 31
	v_lshl_add_u64 v[186:187], v[184:185], 2, s[6:7]
	v_mov_b32_e32 v185, s2
	v_lshl_add_u64 v[188:189], v[184:185], 2, s[6:7]
	s_mov_b64 s[2:3], 0xc0
	v_lshl_add_u64 v[194:195], v[188:189], 0, s[2:3]
	s_lshl_b32 s2, s8, 2
	s_lshl_b32 s9, s12, 10
	s_add_i32 s2, s2, 0
	s_add_i32 s2, s2, s9
	s_add_i32 s6, s2, 0x20c00
	v_readlane_b32 s2, v254, 57
	s_movk_i32 s7, 0x1600
	v_lshlrev_b32_e32 v6, 3, v1
	v_cmp_eq_u32_e64 s[4:5], 0, v1
	v_lshl_add_u32 v209, v0, 2, s2
	v_lshrrev_b32_e32 v1, 1, v8
	v_mul_lo_u32 v0, v9, s7
	v_add_u32_e32 v185, s2, v3
	v_mad_u64_u32 v[0:1], s[2:3], v1, s97, v[0:1]
	v_or_b32_e32 v0, v0, v10
	v_lshl_or_b32 v205, s8, 5, v6
	v_add_lshl_u32 v0, v0, v11, 1
	v_mov_b32_e32 v1, v177
	s_mov_b64 s[8:9], 0x160080
	v_lshl_add_u64 v[196:197], v[0:1], 0, s[8:9]
	v_lshrrev_b32_e32 v1, 1, v12
	v_mul_lo_u32 v0, v13, s7
	v_mad_u64_u32 v[0:1], s[2:3], v1, s97, v[0:1]
	s_waitcnt vmcnt(6)
	s_cmp_eq_u64 s[16:17], 0
	v_or_b32_e32 v0, v0, v14
	s_cselect_b64 s[54:55], -1, 0
	s_cmp_lg_u64 s[16:17], 0
	v_add_lshl_u32 v0, v0, v16, 1
	v_mov_b32_e32 v1, v177
	s_mov_b32 s58, 0
	v_lshl_add_u64 v[190:191], v[188:189], 0, 64
	v_lshl_add_u64 v[192:193], v[188:189], 0, s[74:75]
	s_cselect_b64 s[56:57], -1, 0
	v_add_u32_e32 v206, 64, v185
	v_add_u32_e32 v207, 0x80, v185
	v_add_u32_e32 v208, 0xc0, v185
	v_add_u32_e32 v220, 64, v209
	v_add_u32_e32 v221, 0x80, v209
	v_add_u32_e32 v222, 0xc0, v209
	v_lshl_add_u64 v[198:199], v[0:1], 0, s[8:9]
	v_add_u32_e32 v223, 0, v4
	v_add_u32_e32 v224, s6, v2
	s_mov_b32 s60, s94
	s_mov_b32 s62, s90
	s_mov_b64 s[68:69], s[0:1]
	s_barrier
	s_branch .LBB0_1157
	s_nop 0
	s_nop 0
	s_nop 0
	s_nop 0
	s_nop 0
	s_nop 0
	s_nop 0
	s_nop 0
	s_nop 0
	s_nop 0
	s_nop 0
	s_nop 0
	s_nop 0
	s_nop 0
	s_nop 0
